# adds: no grid barrier before the layer-1 weight-conversion phase (it reads only parameters; next barrier orders everything)
# speedup vs baseline: 1.0031x; 1.0031x over previous
; __device__ __forceinline__ void xcd_barrier(const XcdBarrier& b) {
;     asm volatile("s_waitcnt vmcnt(0)" ::: "memory");
;     __syncthreads();
;     if (threadIdx.x == 0) {
;         unsigned* bar = b.bar; asm volatile("" : "+s"(bar));
;         __builtin_amdgcn_s_waitcnt(0);
;         unsigned nloc = b.st[0], nx = b.st[1];
;         if (nloc == 0u) { xcd_barrier_complete(bar, b.x, nloc, nx); b.st[0] = nloc; b.st[1] = nx; }
; __global__ void __launch_bounds__(512, 2) fwd_kernel(Params p) {
;     ...
;     for (int ph = p.ph_lo; ph < p.ph_hi; ++ph) {
;         if (ph > p.ph_lo) { if (p.ph_hi < 0) grid.sync(); else xcd_barrier(xbar); }
.LBB0_29:
	s_cmp_le_i32 s84, s73
	s_cbranch_scc1 .LBB0_89
	s_cmp_eq_u32 s84, 10
	s_cbranch_scc1 .LBB0_89
	s_mov_b64 s[0:1], -1
	s_and_b64 vcc, exec, s[88:89]
	s_cbranch_vccz .LBB0_76
	s_waitcnt vmcnt(0)
	s_barrier
	s_and_saveexec_b64 s[0:1], s[76:77]
	s_cbranch_execz .LBB0_75
	s_waitcnt lgkmcnt(0)
	v_readlane_b32 s4, v250, 2
	v_readlane_b32 s2, v250, 59
	v_readlane_b32 s5, v250, 3
	s_waitcnt vmcnt(0) expcnt(0) lgkmcnt(0)
	v_mov_b32_e32 v0, s2
	ds_read_b32 v2, v0
	v_readlane_b32 s2, v250, 60
	s_waitcnt lgkmcnt(0)
	v_cmp_ne_u32_e32 vcc, 0, v2
	v_mov_b32_e32 v0, s2
	ds_read_b32 v0, v0
	s_cbranch_vccnz .LBB0_46
	s_add_u32 s8, s4, 0x1000
	s_addc_u32 s9, s5, 0
	s_add_u32 s10, s4, 0x1100
	s_addc_u32 s11, s5, 0
	s_add_u32 s12, s4, 0x1200
	s_addc_u32 s13, s5, 0
	s_add_u32 s14, s4, 0x1300
	s_addc_u32 s15, s5, 0
	s_mov_b32 s2, 1
	s_mov_b64 s[6:7], 0
	v_mov_b64_e32 v[2:3], s[4:5]
	v_mov_b64_e32 v[4:5], s[8:9]
	v_mov_b64_e32 v[6:7], s[10:11]
	v_mov_b64_e32 v[8:9], s[12:13]
	v_mov_b64_e32 v[10:11], s[14:15]
	s_branch .LBB0_36
